# attention loop: one lgkmcnt wait per P.V slice instead of one per MFMA
# baseline (speedup 1.0000x reference)
; #define SBAR() __builtin_amdgcn_sched_barrier(0)
; #define SLOAD(i, k0) do { const char* vt_ = (const char*)Vh + (size_t)(k0) * 256; const char* kt_ = (const char*)Kh + (size_t)(k0) * 128; \
;     sr_[i].vs0 = *reinterpret_cast<const bf16x8*>(vt_ + voff0); sr_[i].vs1 = *reinterpret_cast<const bf16x8*>(vt_ + 32 * 256 + voff0); \
;     sr_[i].ks0 = *reinterpret_cast<const bf16x8*>(kt_ + koff0); } while (0)
; #define SBAR() __builtin_amdgcn_sched_barrier(0)
; template <int KS> __device__ __forceinline__ void pv_ks(f32x16* o, int vb, bf16x8 pa) {
;     const s16x4 l0 = tr_read<v_rd_off(0, KS, 0)>(vb), h0 = tr_read<v_rd_off(0, KS, 1)>(vb), l1 = tr_read<v_rd_off(1, KS, 0)>(vb), h1 = tr_read<v_rd_off(1, KS, 1)>(vb);
;     const s16x4 l2 = tr_read<v_rd_off(2, KS, 0)>(vb), h2 = tr_read<v_rd_off(2, KS, 1)>(vb), l3 = tr_read<v_rd_off(3, KS, 0)>(vb), h3 = tr_read<v_rd_off(3, KS, 1)>(vb);
;     asm volatile("s_waitcnt lgkmcnt(0)" ::: "memory"); SBAR();
;     ...
;     o[0] = __builtin_amdgcn_mfma_f32_32x32x16_bf16(pa, PK(l0, h0), o[0], 0, 0, 0);
;     o[1] = __builtin_amdgcn_mfma_f32_32x32x16_bf16(pa, PK(l1, h1), o[1], 0, 0, 0);
;     o[2] = __builtin_amdgcn_mfma_f32_32x32x16_bf16(pa, PK(l2, h2), o[2], 0, 0, 0);
;     o[3] = __builtin_amdgcn_mfma_f32_32x32x16_bf16(pa, PK(l3, h3), o[3], 0, 0, 0);
;     ...
; }
; __device__ __forceinline__ void attn_unit(const bf16* __restrict__ Qb, const bf16* __restrict__ Kh, const bf16* __restrict__ Vh, bf16* __restrict__ Ob, int seq, char* lds) {
;     ...
;         SBAR(); qkt(pB0, pB1, K_lds + SHM_K, qr, r32, hi); pv_ks<0>(o, vb0, pa0); SBAR();
;         softHalf(pA1, l_reg, pa2, pa3); SBAR();
;         SLOAD(SO, (j + 1) * KVBLK); SBAR();
;         pv_ks<1>(o, vb0, pa1); pv_ks<2>(o, vb0, pa2); pv_ks<3>(o, vb0, pa3); SBAR();
;         softHalf(pB0, l_reg, pa0, pa1); SBAR();
.LBB0_531:
	ds_read_b128 v[82:85], v157 offset:40960
	ds_read_b128 v[86:89], v157 offset:45056
	ds_read_b128 v[164:167], v159 offset:40960
	ds_read_b128 v[168:171], v159 offset:45056
	ds_read_b128 v[188:191], v162 offset:40960
	ds_read_b128 v[230:233], v162 offset:45056
	ds_read_b128 v[234:237], v163 offset:40960
	ds_read_b128 v[242:245], v163 offset:45056
	v_exp_f32_e32 v66, v66
	v_exp_f32_e32 v67, v67
	v_exp_f32_e32 v68, v68
	v_exp_f32_e32 v69, v69
	s_waitcnt lgkmcnt(7)
	v_mfma_f32_32x32x16_bf16 v[98:113], v[82:85], v[126:129], 0
	v_exp_f32_e32 v70, v70
	v_add_f32_e32 v179, 0, v66
	v_exp_f32_e32 v71, v71
	s_waitcnt lgkmcnt(6)
	v_mfma_f32_32x32x16_bf16 v[82:97], v[86:89], v[126:129], 0
	v_add_f32_e32 v179, v67, v179
	v_exp_f32_e32 v72, v72
	v_add_f32_e32 v179, v68, v179
	v_exp_f32_e32 v73, v73
	s_waitcnt lgkmcnt(4)
	v_mfma_f32_32x32x16_bf16 v[98:113], v[164:167], v[122:125], v[98:113]
	v_add_f32_e32 v179, v69, v179
	v_exp_f32_e32 v74, v74
	v_add_f32_e32 v179, v70, v179
	v_exp_f32_e32 v75, v75
	v_mfma_f32_32x32x16_bf16 v[82:97], v[168:171], v[122:125], v[82:97]
	ds_read_b64_tr_b16 v[172:173], v156 offset:0
	ds_read_b64_tr_b16 v[174:175], v156 offset:0x800
	ds_read_b64_tr_b16 v[164:165], v156 offset:0x200
	ds_read_b64_tr_b16 v[166:167], v156 offset:0xa00
	ds_read_b64_tr_b16 v[180:181], v156 offset:0x400
	ds_read_b64_tr_b16 v[182:183], v156 offset:0xc00
	ds_read_b64_tr_b16 v[184:185], v156 offset:0x600
	ds_read_b64_tr_b16 v[186:187], v156 offset:0xe00
	v_add_f32_e32 v179, v71, v179
	v_exp_f32_e32 v76, v76
	v_add_f32_e32 v179, v72, v179
	s_waitcnt lgkmcnt(10)
	v_mfma_f32_32x32x16_bf16 v[98:113], v[188:191], v[118:121], v[98:113]
	v_exp_f32_e32 v77, v77
	v_add_f32_e32 v179, v73, v179
	v_exp_f32_e32 v78, v78
	v_add_f32_e32 v179, v74, v179
	v_mfma_f32_32x32x16_bf16 v[82:97], v[230:233], v[118:121], v[82:97]
	v_exp_f32_e32 v79, v79
	v_add_f32_e32 v179, v75, v179
	v_exp_f32_e32 v80, v80
	s_waitcnt lgkmcnt(8)
	v_mfma_f32_32x32x16_bf16 v[98:113], v[234:237], v[114:117], v[98:113]
	v_add_f32_e32 v179, v76, v179
	v_exp_f32_e32 v81, v81
	v_add_f32_e32 v179, v77, v179
	v_add_f32_e32 v179, v78, v179
	v_add_f32_e32 v179, v79, v179
	v_mfma_f32_32x32x16_bf16 v[82:97], v[242:245], v[114:117], v[82:97]
	v_add_f32_e32 v179, v80, v179
	v_add_f32_e32 v179, v81, v179
	v_cvt_pk_bf16_f32 v66, v66, v67
	v_cvt_pk_bf16_f32 v67, v68, v69
	s_waitcnt lgkmcnt(0)
	v_mfma_f32_32x32x16_bf16 v[2:17], v[134:137], v[172:175], v[2:17]
	ds_read_b64_tr_b16 v[188:189], v156 offset:0x1000
	ds_read_b64_tr_b16 v[190:191], v156 offset:0x1800
	ds_read_b64_tr_b16 v[230:231], v156 offset:0x1200
	ds_read_b64_tr_b16 v[232:233], v156 offset:0x1a00
	ds_read_b64_tr_b16 v[234:235], v156 offset:0x1400
	ds_read_b64_tr_b16 v[236:237], v156 offset:0x1c00
	ds_read_b64_tr_b16 v[242:243], v156 offset:0x1600
	ds_read_b64_tr_b16 v[244:245], v156 offset:0x1e00
	v_cvt_pk_bf16_f32 v68, v70, v71
	v_cvt_pk_bf16_f32 v69, v72, v73
	v_cvt_pk_bf16_f32 v70, v74, v75
	v_cvt_pk_bf16_f32 v71, v76, v77
	v_cvt_pk_bf16_f32 v72, v78, v79
	v_mfma_f32_32x32x16_bf16 v[18:33], v[134:137], v[164:167], v[18:33]
	v_cvt_pk_bf16_f32 v73, v80, v81
	v_add_f32_e32 v221, v139, v179
	v_permlane32_swap_b32_e32 v66, v68
	v_mfma_f32_32x32x16_bf16 v[34:49], v[134:137], v[180:183], v[34:49]
	v_permlane32_swap_b32_e32 v67, v69
	v_permlane32_swap_b32_e32 v70, v72
	v_permlane32_swap_b32_e32 v71, v73
	v_mfma_f32_32x32x16_bf16 v[50:65], v[134:137], v[184:187], v[50:65]
	v_lshl_add_u64 v[136:137], s[30:31], 0, v[148:149]
	v_add_co_u32_e32 v74, vcc, s40, v136
	v_lshl_add_u64 v[150:151], s[30:31], 0, v[146:147]
	s_nop 0
	v_addc_co_u32_e32 v75, vcc, 0, v137, vcc
	v_add_co_u32_e32 v78, vcc, s41, v136
	s_nop 1
	v_addc_co_u32_e32 v79, vcc, 0, v137, vcc
	v_add_co_u32_e32 v164, vcc, s42, v150
	global_load_dwordx4 v[74:77], v[74:75], off
	s_waitcnt lgkmcnt(0)
	v_mfma_f32_32x32x16_bf16 v[2:17], v[130:133], v[188:191], v[2:17]
	ds_read_b64_tr_b16 v[168:169], v156 offset:0x2000
	ds_read_b64_tr_b16 v[170:171], v156 offset:0x2800
	ds_read_b64_tr_b16 v[172:173], v156 offset:0x2200
	ds_read_b64_tr_b16 v[174:175], v156 offset:0x2a00
	ds_read_b64_tr_b16 v[180:181], v156 offset:0x2400
	ds_read_b64_tr_b16 v[182:183], v156 offset:0x2c00
	ds_read_b64_tr_b16 v[184:185], v156 offset:0x2600
	ds_read_b64_tr_b16 v[186:187], v156 offset:0x2e00
	s_nop 0
	global_load_dwordx4 v[78:81], v[78:79], off
	v_addc_co_u32_e32 v165, vcc, 0, v151, vcc
	global_load_dwordx4 v[164:167], v[164:165], off
	v_exp_f32_e32 v220, v98
	v_mfma_f32_32x32x16_bf16 v[18:33], v[130:133], v[230:233], v[18:33]
	v_exp_f32_e32 v177, v99
	v_exp_f32_e32 v193, v100
	v_exp_f32_e32 v195, v101
	v_mfma_f32_32x32x16_bf16 v[34:49], v[130:133], v[234:237], v[34:49]
	v_exp_f32_e32 v197, v102
	v_exp_f32_e32 v199, v103
	v_exp_f32_e32 v201, v104
	v_exp_f32_e32 v203, v105
	v_mfma_f32_32x32x16_bf16 v[50:65], v[130:133], v[242:245], v[50:65]
	v_cvt_pk_bf16_f32 v222, v220, v177
	v_cvt_pk_bf16_f32 v223, v193, v195
	v_cvt_pk_bf16_f32 v224, v197, v199
	v_cvt_pk_bf16_f32 v225, v201, v203
	v_exp_f32_e32 v205, v106
	s_waitcnt lgkmcnt(0)
	v_mfma_f32_32x32x16_bf16 v[2:17], v[66:69], v[168:171], v[2:17]
	ds_read_b64_tr_b16 v[188:189], v156 offset:0x3000
	ds_read_b64_tr_b16 v[190:191], v156 offset:0x3800
	ds_read_b64_tr_b16 v[230:231], v156 offset:0x3200
	ds_read_b64_tr_b16 v[232:233], v156 offset:0x3a00
	ds_read_b64_tr_b16 v[234:235], v156 offset:0x3400
	ds_read_b64_tr_b16 v[236:237], v156 offset:0x3c00
	ds_read_b64_tr_b16 v[242:243], v156 offset:0x3600
	ds_read_b64_tr_b16 v[244:245], v156 offset:0x3e00
	v_exp_f32_e32 v207, v107
	v_exp_f32_e32 v209, v108
	v_exp_f32_e32 v211, v109
	v_mfma_f32_32x32x16_bf16 v[18:33], v[66:69], v[172:175], v[18:33]
	v_exp_f32_e32 v213, v110
	v_exp_f32_e32 v215, v111
	v_exp_f32_e32 v217, v112
	v_mfma_f32_32x32x16_bf16 v[34:49], v[66:69], v[180:183], v[34:49]
	v_exp_f32_e32 v219, v113
	v_add_f32_e32 v139, 0, v220
	v_add_f32_e32 v238, v177, v139
	v_add_f32_e32 v238, v193, v238
	v_add_f32_e32 v238, v195, v238
	v_add_f32_e32 v238, v197, v238
	v_mfma_f32_32x32x16_bf16 v[50:65], v[66:69], v[184:187], v[50:65]
	v_add_f32_e32 v238, v199, v238
	v_add_f32_e32 v238, v201, v238
	v_add_f32_e32 v238, v203, v238
	v_add_f32_e32 v238, v205, v238
	v_add_f32_e32 v238, v207, v238
	v_add_f32_e32 v238, v209, v238
	s_waitcnt lgkmcnt(0)
	v_mfma_f32_32x32x16_bf16 v[2:17], v[70:73], v[188:191], v[2:17]
	v_add_f32_e32 v238, v211, v238
	v_add_f32_e32 v238, v213, v238
	v_add_f32_e32 v238, v215, v238
	v_add_f32_e32 v238, v217, v238
	v_add_f32_e32 v238, v219, v238
	v_add_f32_e32 v238, v221, v238
	v_mfma_f32_32x32x16_bf16 v[18:33], v[70:73], v[230:233], v[18:33]
	v_permlane32_swap_b32_e32 v222, v224
	v_permlane32_swap_b32_e32 v223, v225
	v_cvt_pk_bf16_f32 v226, v205, v207
	v_cvt_pk_bf16_f32 v227, v209, v211
	v_cvt_pk_bf16_f32 v228, v213, v215
	v_mfma_f32_32x32x16_bf16 v[34:49], v[70:73], v[234:237], v[34:49]
	v_cvt_pk_bf16_f32 v229, v217, v219
	s_nop 0
	v_permlane32_swap_b32_e32 v226, v228
	v_permlane32_swap_b32_e32 v227, v229
	v_mfma_f32_32x32x16_bf16 v[50:65], v[70:73], v[242:245], v[50:65]
	s_barrier
; #define SBAR() __builtin_amdgcn_sched_barrier(0)
; #define SLOAD(i, k0) do { const char* vt_ = (const char*)Vh + (size_t)(k0) * 256; const char* kt_ = (const char*)Kh + (size_t)(k0) * 128; \
;     sr_[i].vs0 = *reinterpret_cast<const bf16x8*>(vt_ + voff0); sr_[i].vs1 = *reinterpret_cast<const bf16x8*>(vt_ + 32 * 256 + voff0); \
;     sr_[i].ks0 = *reinterpret_cast<const bf16x8*>(kt_ + koff0); } while (0)
; #define SWRITE(b, i) do { *(bf16x8*)(V_lds + (b) * SHM_V + vst0) = sr_[i].vs0; *(bf16x8*)(V_lds + (b) * SHM_V + vst1) = sr_[i].vs1; \
;     *(bf16x8*)(K_lds + (b) * SHM_K + kst) = sr_[i].ks0; } while (0)
; #define SWAIT() asm volatile("s_waitcnt vmcnt(0)" ::: "memory")
; #define SBAR() __builtin_amdgcn_sched_barrier(0)
; __device__ __forceinline__ void attn_unit(const bf16* __restrict__ Qb, const bf16* __restrict__ Kh, const bf16* __restrict__ Vh, bf16* __restrict__ Ob, int seq, char* lds) {
;     ...
;         __syncthreads(); SWAIT(); SWRITE(0, SE);
;         __syncthreads();
;         SBAR(); qkt(pA0, pA1, K_lds, qr, r32, hi); pv_ks<0>(o, vb0 + SHM_V, pa0); SBAR();
;         softHalf(pB1, l_reg, pa2, pa3); SBAR();
;         SLOAD(SE, (j + 2) * KVBLK); SBAR();
;         pv_ks<1>(o, vb0 + SHM_V, pa1); pv_ks<2>(o, vb0 + SHM_V, pa2); pv_ks<3>(o, vb0 + SHM_V, pa3); SBAR();
;         softHalf(pA0, l_reg, pa0, pa1); SBAR();
	s_waitcnt vmcnt(0)
	s_waitcnt vmcnt(2)
	ds_write_b128 v160, v[74:77]
	s_waitcnt vmcnt(1)
	ds_write_b128 v161, v[78:81]
	s_waitcnt vmcnt(0)
	ds_write_b128 v158, v[164:167] offset:32768
	s_waitcnt lgkmcnt(0)
	s_barrier
	ds_read_b128 v[66:69], v157 offset:32768
	ds_read_b128 v[70:73], v157 offset:36864
	ds_read_b128 v[164:167], v159 offset:32768
	ds_read_b128 v[172:175], v159 offset:36864
	ds_read_b128 v[230:233], v162 offset:32768
	ds_read_b128 v[234:237], v162 offset:36864
	ds_read_b128 v[168:171], v163 offset:32768
	ds_read_b128 v[242:245], v163 offset:36864
	v_exp_f32_e32 v176, v82
	v_exp_f32_e32 v192, v83
	v_exp_f32_e32 v194, v84
	v_exp_f32_e32 v196, v85
	s_waitcnt lgkmcnt(7)
	v_mfma_f32_32x32x16_bf16 v[98:113], v[66:69], v[126:129], 0
	v_exp_f32_e32 v198, v86
	v_add_f32_e32 v82, v176, v138
	v_exp_f32_e32 v200, v87
	v_add_f32_e32 v82, v192, v82
	s_waitcnt lgkmcnt(6)
	v_mfma_f32_32x32x16_bf16 v[66:81], v[70:73], v[126:129], 0
	v_exp_f32_e32 v202, v88
	v_add_f32_e32 v82, v194, v82
	v_exp_f32_e32 v204, v89
	s_waitcnt lgkmcnt(4)
	v_mfma_f32_32x32x16_bf16 v[98:113], v[164:167], v[122:125], v[98:113]
	v_add_f32_e32 v82, v196, v82
	v_exp_f32_e32 v206, v90
	v_add_f32_e32 v82, v198, v82
	v_exp_f32_e32 v208, v91
	v_mfma_f32_32x32x16_bf16 v[66:81], v[172:175], v[122:125], v[66:81]
	ds_read_b64_tr_b16 v[180:181], v141 offset:0
	ds_read_b64_tr_b16 v[182:183], v141 offset:0x800
	ds_read_b64_tr_b16 v[164:165], v141 offset:0x200
	ds_read_b64_tr_b16 v[166:167], v141 offset:0xa00
	ds_read_b64_tr_b16 v[184:185], v141 offset:0x400
	ds_read_b64_tr_b16 v[186:187], v141 offset:0xc00
	ds_read_b64_tr_b16 v[188:189], v141 offset:0x600
	ds_read_b64_tr_b16 v[190:191], v141 offset:0xe00
	v_add_f32_e32 v82, v200, v82
	v_exp_f32_e32 v210, v92
	v_add_f32_e32 v82, v202, v82
	s_waitcnt lgkmcnt(10)
	v_mfma_f32_32x32x16_bf16 v[98:113], v[230:233], v[118:121], v[98:113]
	v_exp_f32_e32 v212, v93
	v_add_f32_e32 v82, v204, v82
	v_exp_f32_e32 v214, v94
	v_add_f32_e32 v82, v206, v82
	v_mfma_f32_32x32x16_bf16 v[66:81], v[234:237], v[118:121], v[66:81]
	v_exp_f32_e32 v216, v95
	v_add_f32_e32 v82, v208, v82
	v_exp_f32_e32 v218, v96
	v_add_f32_e32 v82, v210, v82
	s_waitcnt lgkmcnt(8)
	v_mfma_f32_32x32x16_bf16 v[98:113], v[168:171], v[114:117], v[98:113]
	v_exp_f32_e32 v220, v97
	v_add_f32_e32 v82, v212, v82
	v_add_f32_e32 v82, v214, v82
	v_add_f32_e32 v82, v216, v82
	v_mfma_f32_32x32x16_bf16 v[66:81], v[242:245], v[114:117], v[66:81]
	v_add_f32_e32 v82, v218, v82
	v_add_f32_e32 v82, v220, v82
	v_add_f32_e32 v139, v82, v238
	v_cvt_pk_bf16_f32 v82, v176, v192
	v_cvt_pk_bf16_f32 v83, v194, v196
	s_waitcnt lgkmcnt(0)
	v_mfma_f32_32x32x16_bf16 v[2:17], v[222:225], v[180:183], v[2:17]
	ds_read_b64_tr_b16 v[230:231], v141 offset:0x1000
	ds_read_b64_tr_b16 v[232:233], v141 offset:0x1800
	ds_read_b64_tr_b16 v[234:235], v141 offset:0x1200
	ds_read_b64_tr_b16 v[236:237], v141 offset:0x1a00
	ds_read_b64_tr_b16 v[168:169], v141 offset:0x1400
	ds_read_b64_tr_b16 v[170:171], v141 offset:0x1c00
	ds_read_b64_tr_b16 v[172:173], v141 offset:0x1600
	ds_read_b64_tr_b16 v[174:175], v141 offset:0x1e00
	v_cvt_pk_bf16_f32 v84, v198, v200
	v_cvt_pk_bf16_f32 v85, v202, v204
	v_cvt_pk_bf16_f32 v86, v206, v208
	v_cvt_pk_bf16_f32 v87, v210, v212
	v_mfma_f32_32x32x16_bf16 v[18:33], v[222:225], v[164:167], v[18:33]
	v_cvt_pk_bf16_f32 v88, v214, v216
	v_cvt_pk_bf16_f32 v89, v218, v220
	s_nop 0
	v_permlane32_swap_b32_e32 v82, v84
	v_mfma_f32_32x32x16_bf16 v[34:49], v[222:225], v[184:187], v[34:49]
	v_permlane32_swap_b32_e32 v83, v85
	v_permlane32_swap_b32_e32 v86, v88
	v_permlane32_swap_b32_e32 v87, v89
	v_mfma_f32_32x32x16_bf16 v[50:65], v[222:225], v[188:191], v[50:65]
	v_add_co_u32_e32 v90, vcc, s43, v136
	s_nop 1
	v_addc_co_u32_e32 v91, vcc, 0, v137, vcc
	v_add_co_u32_e32 v94, vcc, s46, v136
	s_nop 1
	v_addc_co_u32_e32 v95, vcc, 0, v137, vcc
	v_add_co_u32_e32 v130, vcc, s47, v150
	global_load_dwordx4 v[90:93], v[90:91], off
	s_nop 0
	s_waitcnt lgkmcnt(0)
	v_mfma_f32_32x32x16_bf16 v[2:17], v[226:229], v[230:233], v[2:17]
	ds_read_b64_tr_b16 v[180:181], v141 offset:0x2000
	ds_read_b64_tr_b16 v[182:183], v141 offset:0x2800
	ds_read_b64_tr_b16 v[184:185], v141 offset:0x2200
	ds_read_b64_tr_b16 v[186:187], v141 offset:0x2a00
	ds_read_b64_tr_b16 v[188:189], v141 offset:0x2400
	ds_read_b64_tr_b16 v[190:191], v141 offset:0x2c00
	ds_read_b64_tr_b16 v[222:223], v141 offset:0x2600
	ds_read_b64_tr_b16 v[224:225], v141 offset:0x2e00
	global_load_dwordx4 v[94:97], v[94:95], off
	v_addc_co_u32_e32 v131, vcc, 0, v151, vcc
	global_load_dwordx4 v[164:167], v[130:131], off
	v_exp_f32_e32 v239, v98
	v_exp_f32_e32 v241, v99
	v_mfma_f32_32x32x16_bf16 v[18:33], v[226:229], v[234:237], v[18:33]
	v_exp_f32_e32 v242, v100
	v_exp_f32_e32 v243, v101
	v_exp_f32_e32 v244, v102
	v_mfma_f32_32x32x16_bf16 v[34:49], v[226:229], v[168:171], v[34:49]
	v_exp_f32_e32 v98, v106
	v_add_f32_e32 v106, 0, v239
	v_exp_f32_e32 v245, v103
	v_add_f32_e32 v106, v241, v106
	v_mfma_f32_32x32x16_bf16 v[50:65], v[226:229], v[172:175], v[50:65]
	v_exp_f32_e32 v246, v104
	v_add_f32_e32 v106, v242, v106
	v_exp_f32_e32 v247, v105
	v_add_f32_e32 v106, v243, v106
	v_add_f32_e32 v106, v244, v106
	s_waitcnt lgkmcnt(0)
; #define SBAR() __builtin_amdgcn_sched_barrier(0)
; #define SWRITE(b, i) do { *(bf16x8*)(V_lds + (b) * SHM_V + vst0) = sr_[i].vs0; *(bf16x8*)(V_lds + (b) * SHM_V + vst1) = sr_[i].vs1; \
;     *(bf16x8*)(K_lds + (b) * SHM_K + kst) = sr_[i].ks0; } while (0)
; #define SWAIT() asm volatile("s_waitcnt vmcnt(0)" ::: "memory")
; #define SBAR() __builtin_amdgcn_sched_barrier(0)
; __device__ __forceinline__ void attn_unit(const bf16* __restrict__ Qb, const bf16* __restrict__ Kh, const bf16* __restrict__ Vh, bf16* __restrict__ Ob, int seq, char* lds) {
;     ...
;         pv_ks<1>(o, vb0 + SHM_V, pa1); pv_ks<2>(o, vb0 + SHM_V, pa2); pv_ks<3>(o, vb0 + SHM_V, pa3); SBAR();
;         softHalf(pA0, l_reg, pa0, pa1); SBAR();
;         __syncthreads(); SWAIT(); SWRITE(1, SO);
;         __syncthreads();
;     }
;     SBAR(); qkt(pB0, pB1, K_lds + SHM_K, qr, r32, hi); pv_ks<0>(o, vb0, pa0); SBAR();
;     softHalf(pA1, l_reg, pa2, pa3); SBAR();
;     pv_ks<1>(o, vb0, pa1); pv_ks<2>(o, vb0, pa2); pv_ks<3>(o, vb0, pa3); SBAR();
	v_mfma_f32_32x32x16_bf16 v[2:17], v[82:85], v[180:183], v[2:17]
	ds_read_b64_tr_b16 v[230:231], v141 offset:0x3000
	ds_read_b64_tr_b16 v[232:233], v141 offset:0x3800
	ds_read_b64_tr_b16 v[234:235], v141 offset:0x3200
	ds_read_b64_tr_b16 v[236:237], v141 offset:0x3a00
	ds_read_b64_tr_b16 v[168:169], v141 offset:0x3400
	ds_read_b64_tr_b16 v[170:171], v141 offset:0x3c00
	ds_read_b64_tr_b16 v[172:173], v141 offset:0x3600
	ds_read_b64_tr_b16 v[174:175], v141 offset:0x3e00
	v_exp_f32_e32 v99, v107
	v_add_f32_e32 v106, v245, v106
	v_exp_f32_e32 v100, v108
	v_add_f32_e32 v106, v246, v106
	v_mfma_f32_32x32x16_bf16 v[18:33], v[82:85], v[184:187], v[18:33]
	v_exp_f32_e32 v101, v109
	v_add_f32_e32 v106, v247, v106
	v_exp_f32_e32 v102, v110
	v_add_f32_e32 v106, v98, v106
	v_mfma_f32_32x32x16_bf16 v[34:49], v[82:85], v[188:191], v[34:49]
	v_exp_f32_e32 v103, v111
	v_add_f32_e32 v106, v99, v106
	v_exp_f32_e32 v104, v112
	v_add_f32_e32 v106, v100, v106
	v_mfma_f32_32x32x16_bf16 v[50:65], v[82:85], v[222:225], v[50:65]
	v_exp_f32_e32 v105, v113
	v_add_f32_e32 v106, v101, v106
	v_add_f32_e32 v106, v102, v106
	v_add_f32_e32 v106, v103, v106
	v_add_f32_e32 v106, v104, v106
	v_add_f32_e32 v106, v105, v106
	s_waitcnt lgkmcnt(0)
	v_mfma_f32_32x32x16_bf16 v[2:17], v[86:89], v[230:233], v[2:17]
	v_cvt_pk_bf16_f32 v134, v239, v241
	v_cvt_pk_bf16_f32 v135, v242, v243
	v_cvt_pk_bf16_f32 v136, v244, v245
	v_cvt_pk_bf16_f32 v137, v246, v247
	v_cvt_pk_bf16_f32 v130, v98, v99
	v_mfma_f32_32x32x16_bf16 v[18:33], v[86:89], v[234:237], v[18:33]
	v_cvt_pk_bf16_f32 v131, v100, v101
	v_cvt_pk_bf16_f32 v132, v102, v103
	v_cvt_pk_bf16_f32 v133, v104, v105
	v_add_f32_e32 v139, v139, v106
	v_permlane32_swap_b32_e32 v134, v136
	v_mfma_f32_32x32x16_bf16 v[34:49], v[86:89], v[168:171], v[34:49]
	v_permlane32_swap_b32_e32 v135, v137
	v_permlane32_swap_b32_e32 v130, v132
	v_permlane32_swap_b32_e32 v131, v133
	v_mfma_f32_32x32x16_bf16 v[50:65], v[86:89], v[172:175], v[50:65]
	s_barrier
	s_waitcnt vmcnt(0)
	s_add_i32 s10, s10, 2
	v_lshl_add_u64 v[146:147], v[146:147], 0, s[0:1]
	s_cmp_gt_u32 s10, 32
	v_lshl_add_u64 v[148:149], v[148:149], 0, s[4:5]
	s_waitcnt vmcnt(2)
	ds_write_b128 v160, v[90:93] offset:16384
	s_waitcnt vmcnt(1)
	ds_write_b128 v161, v[94:97] offset:16384
	s_waitcnt vmcnt(0)
	ds_write_b128 v158, v[164:167] offset:40960
	s_waitcnt lgkmcnt(0)
	s_barrier
	s_cbranch_scc0 .LBB0_531
	v_and_b32_e32 v82, 0x3fffffc0, v143
	v_lshl_add_u32 v143, v82, 2, 0
	ds_read_b128 v[82:85], v157 offset:40960
	ds_read_b128 v[86:89], v157 offset:45056
	s_waitcnt lgkmcnt(1)
	v_mfma_f32_32x32x16_bf16 v[98:113], v[82:85], v[126:129], 0
	s_waitcnt lgkmcnt(0)
	v_mfma_f32_32x32x16_bf16 v[82:97], v[86:89], v[126:129], 0
	ds_read_b128 v[126:129], v159 offset:40960
	ds_read_b128 v[146:149], v159 offset:45056
	s_waitcnt lgkmcnt(1)
	v_mfma_f32_32x32x16_bf16 v[98:113], v[126:129], v[122:125], v[98:113]
	s_waitcnt lgkmcnt(0)
	v_mfma_f32_32x32x16_bf16 v[82:97], v[146:149], v[122:125], v[82:97]
	ds_read_b128 v[122:125], v162 offset:40960
	ds_read_b128 v[126:129], v162 offset:45056
	s_waitcnt lgkmcnt(1)
	v_mfma_f32_32x32x16_bf16 v[98:113], v[122:125], v[118:121], v[98:113]
	s_waitcnt lgkmcnt(0)
	v_mfma_f32_32x32x16_bf16 v[82:97], v[126:129], v[118:121], v[82:97]
	ds_read_b128 v[118:121], v163 offset:40960
	ds_read_b128 v[122:125], v163 offset:45056
	ds_read_b64_tr_b16 v[126:127], v156 offset:0
	ds_read_b64_tr_b16 v[128:129], v156 offset:0x800
	s_waitcnt lgkmcnt(1)
	v_mfma_f32_32x32x16_bf16 v[98:113], v[118:121], v[114:117], v[98:113]
	ds_read_b64_tr_b16 v[118:119], v156 offset:0x200
	ds_read_b64_tr_b16 v[120:121], v156 offset:0xa00
	ds_read_b64_tr_b16 v[146:147], v156 offset:0x400
	ds_read_b64_tr_b16 v[148:149], v156 offset:0xc00
	ds_read_b64_tr_b16 v[158:159], v156 offset:0x600
	ds_read_b64_tr_b16 v[160:161], v156 offset:0xe00
	s_waitcnt lgkmcnt(0)
	s_waitcnt lgkmcnt(0)
	v_mfma_f32_32x32x16_bf16 v[82:97], v[122:125], v[114:117], v[82:97]
	v_mfma_f32_32x32x16_bf16 v[2:17], v[134:137], v[126:129], v[2:17]
	v_mfma_f32_32x32x16_bf16 v[18:33], v[134:137], v[118:121], v[18:33]
	v_mfma_f32_32x32x16_bf16 v[34:49], v[134:137], v[146:149], v[34:49]
	v_mfma_f32_32x32x16_bf16 v[50:65], v[134:137], v[158:161], v[50:65]
	v_exp_f32_e32 v66, v66
	v_exp_f32_e32 v67, v67
	v_exp_f32_e32 v68, v68
	v_exp_f32_e32 v69, v69
	v_exp_f32_e32 v70, v70
	v_add_f32_e32 v114, 0, v66
	v_exp_f32_e32 v71, v71
	v_add_f32_e32 v114, v67, v114
	v_exp_f32_e32 v72, v72
	v_add_f32_e32 v114, v68, v114
	v_exp_f32_e32 v73, v73
	v_add_f32_e32 v114, v69, v114
	v_exp_f32_e32 v74, v74
	v_add_f32_e32 v114, v70, v114
	v_exp_f32_e32 v75, v75
	v_add_f32_e32 v114, v71, v114
	v_exp_f32_e32 v76, v76
	v_add_f32_e32 v114, v72, v114
	v_exp_f32_e32 v77, v77
	v_add_f32_e32 v114, v73, v114
	v_exp_f32_e32 v78, v78
	v_add_f32_e32 v114, v74, v114
	v_exp_f32_e32 v79, v79
	v_add_f32_e32 v114, v75, v114
	v_exp_f32_e32 v80, v80
	v_add_f32_e32 v114, v76, v114
	v_exp_f32_e32 v81, v81
	v_add_f32_e32 v114, v77, v114
	v_add_f32_e32 v114, v78, v114
	v_add_f32_e32 v114, v79, v114
	v_add_f32_e32 v114, v80, v114
	v_cvt_pk_bf16_f32 v66, v66, v67
	v_cvt_pk_bf16_f32 v67, v68, v69
	v_cvt_pk_bf16_f32 v68, v70, v71
	v_cvt_pk_bf16_f32 v69, v72, v73
	v_add_f32_e32 v114, v81, v114
	v_permlane32_swap_b32_e32 v66, v68
	v_permlane32_swap_b32_e32 v67, v69
	v_cvt_pk_bf16_f32 v70, v74, v75
	v_cvt_pk_bf16_f32 v71, v76, v77
	v_cvt_pk_bf16_f32 v72, v78, v79
	v_cvt_pk_bf16_f32 v73, v80, v81
	v_add_f32_e32 v126, v139, v114
	v_permlane32_swap_b32_e32 v70, v72
	v_permlane32_swap_b32_e32 v71, v73
	ds_read_b64_tr_b16 v[74:75], v156 offset:0x1000
	ds_read_b64_tr_b16 v[76:77], v156 offset:0x1800
	ds_read_b64_tr_b16 v[78:79], v156 offset:0x1200
	ds_read_b64_tr_b16 v[80:81], v156 offset:0x1a00
	ds_read_b64_tr_b16 v[114:115], v156 offset:0x1400
	ds_read_b64_tr_b16 v[116:117], v156 offset:0x1c00
	ds_read_b64_tr_b16 v[118:119], v156 offset:0x1600
	ds_read_b64_tr_b16 v[120:121], v156 offset:0x1e00
	s_waitcnt lgkmcnt(0)
; #define SBAR() __builtin_amdgcn_sched_barrier(0)
; #define SBAR() __builtin_amdgcn_sched_barrier(0)
; __device__ __forceinline__ void attn_unit(const bf16* __restrict__ Qb, const bf16* __restrict__ Kh, const bf16* __restrict__ Vh, bf16* __restrict__ Ob, int seq, char* lds) {
;     ...
;     pv_ks<1>(o, vb0, pa1); pv_ks<2>(o, vb0, pa2); pv_ks<3>(o, vb0, pa3); SBAR();
;     softHalf(pB0, l_reg, pa0, pa1); SBAR();
;     pv_ks<0>(o, vb0 + SHM_V, pa0); SBAR();
	s_nop 0
	v_mfma_f32_32x32x16_bf16 v[2:17], v[130:133], v[74:77], v[2:17]
	ds_read_b64_tr_b16 v[74:75], v156 offset:0x2000
	ds_read_b64_tr_b16 v[76:77], v156 offset:0x2800
	v_mfma_f32_32x32x16_bf16 v[18:33], v[130:133], v[78:81], v[18:33]
	ds_read_b64_tr_b16 v[78:79], v156 offset:0x2200
	ds_read_b64_tr_b16 v[80:81], v156 offset:0x2a00
	v_mfma_f32_32x32x16_bf16 v[34:49], v[130:133], v[114:117], v[34:49]
	ds_read_b64_tr_b16 v[114:115], v156 offset:0x2400
	ds_read_b64_tr_b16 v[116:117], v156 offset:0x2c00
	ds_read_b64_tr_b16 v[122:123], v156 offset:0x2600
	ds_read_b64_tr_b16 v[124:125], v156 offset:0x2e00
	s_waitcnt lgkmcnt(0)
	v_mfma_f32_32x32x16_bf16 v[50:65], v[130:133], v[118:121], v[50:65]
	v_mfma_f32_32x32x16_bf16 v[2:17], v[66:69], v[74:77], v[2:17]
	ds_read_b64_tr_b16 v[74:75], v156 offset:0x3000
	ds_read_b64_tr_b16 v[76:77], v156 offset:0x3800
	v_mfma_f32_32x32x16_bf16 v[18:33], v[66:69], v[78:81], v[18:33]
	ds_read_b64_tr_b16 v[78:79], v156 offset:0x3200
	ds_read_b64_tr_b16 v[80:81], v156 offset:0x3a00
	v_mfma_f32_32x32x16_bf16 v[34:49], v[66:69], v[114:117], v[34:49]
	ds_read_b64_tr_b16 v[114:115], v156 offset:0x3400
	ds_read_b64_tr_b16 v[116:117], v156 offset:0x3c00
	ds_read_b64_tr_b16 v[118:119], v156 offset:0x3600
	ds_read_b64_tr_b16 v[120:121], v156 offset:0x3e00
	s_waitcnt lgkmcnt(0)
	v_mfma_f32_32x32x16_bf16 v[50:65], v[66:69], v[122:125], v[50:65]
	v_mfma_f32_32x32x16_bf16 v[2:17], v[70:73], v[74:77], v[2:17]
	v_mfma_f32_32x32x16_bf16 v[18:33], v[70:73], v[78:81], v[18:33]
	v_mfma_f32_32x32x16_bf16 v[34:49], v[70:73], v[114:117], v[34:49]
	v_mfma_f32_32x32x16_bf16 v[50:65], v[70:73], v[118:121], v[50:65]
	v_exp_f32_e32 v66, v98
	v_exp_f32_e32 v67, v99
	v_exp_f32_e32 v68, v100
	v_exp_f32_e32 v69, v101
	v_exp_f32_e32 v70, v102
	v_add_f32_e32 v98, 0, v66
	v_exp_f32_e32 v71, v103
	v_add_f32_e32 v98, v67, v98
	v_exp_f32_e32 v72, v104
	v_add_f32_e32 v98, v68, v98
	v_exp_f32_e32 v73, v105
	v_add_f32_e32 v98, v69, v98
	v_exp_f32_e32 v74, v106
	v_add_f32_e32 v98, v70, v98
	v_exp_f32_e32 v75, v107
	v_add_f32_e32 v98, v71, v98
	v_exp_f32_e32 v76, v108
	v_add_f32_e32 v98, v72, v98
	v_exp_f32_e32 v77, v109
	v_add_f32_e32 v98, v73, v98
	v_exp_f32_e32 v78, v110
	v_add_f32_e32 v98, v74, v98
	v_exp_f32_e32 v79, v111
	v_add_f32_e32 v98, v75, v98
	v_exp_f32_e32 v80, v112
	v_add_f32_e32 v98, v76, v98
	v_exp_f32_e32 v81, v113
	v_add_f32_e32 v98, v77, v98
	v_add_f32_e32 v98, v78, v98
	v_add_f32_e32 v98, v79, v98
	v_add_f32_e32 v98, v80, v98
	v_cvt_pk_bf16_f32 v66, v66, v67
	v_cvt_pk_bf16_f32 v67, v68, v69
	v_cvt_pk_bf16_f32 v68, v70, v71
	v_cvt_pk_bf16_f32 v69, v72, v73
	v_add_f32_e32 v98, v81, v98
	v_permlane32_swap_b32_e32 v66, v68
	v_permlane32_swap_b32_e32 v67, v69
	v_cvt_pk_bf16_f32 v70, v74, v75
	v_cvt_pk_bf16_f32 v71, v76, v77
	v_cvt_pk_bf16_f32 v72, v78, v79
	v_cvt_pk_bf16_f32 v73, v80, v81
	v_add_f32_e32 v106, v126, v98
	v_permlane32_swap_b32_e32 v70, v72
	v_permlane32_swap_b32_e32 v71, v73
	ds_read_b64_tr_b16 v[74:75], v141 offset:0
	ds_read_b64_tr_b16 v[76:77], v141 offset:0x800
	ds_read_b64_tr_b16 v[78:79], v141 offset:0x200
	ds_read_b64_tr_b16 v[80:81], v141 offset:0xa00
	ds_read_b64_tr_b16 v[98:99], v141 offset:0x400
	ds_read_b64_tr_b16 v[100:101], v141 offset:0xc00
	ds_read_b64_tr_b16 v[102:103], v141 offset:0x600
	ds_read_b64_tr_b16 v[104:105], v141 offset:0xe00
	s_waitcnt lgkmcnt(0)
; #define SBAR() __builtin_amdgcn_sched_barrier(0)
; #define SBAR() __builtin_amdgcn_sched_barrier(0)
; __device__ __forceinline__ void attn_unit(const bf16* __restrict__ Qb, const bf16* __restrict__ Kh, const bf16* __restrict__ Vh, bf16* __restrict__ Ob, int seq, char* lds) {
;     ...
;     pv_ks<0>(o, vb0 + SHM_V, pa0); SBAR();
;     softHalf(pB1, l_reg, pa2, pa3); SBAR();
;     pv_ks<1>(o, vb0 + SHM_V, pa1); pv_ks<2>(o, vb0 + SHM_V, pa2); pv_ks<3>(o, vb0 + SHM_V, pa3);
;     { auto rr = __builtin_amdgcn_permlane32_swap(__float_as_uint(l_reg), __float_as_uint(l_reg), false, false); l_reg = __uint_as_float(rr[0]) + __uint_as_float(rr[1]); }
;     if (hi == 0) wsf[r32] = l_reg; asm volatile("s_waitcnt lgkmcnt(0)" ::: "memory");
	s_nop 0
	v_mfma_f32_32x32x16_bf16 v[2:17], v[66:69], v[74:77], v[2:17]
	v_mfma_f32_32x32x16_bf16 v[18:33], v[66:69], v[78:81], v[18:33]
	v_mfma_f32_32x32x16_bf16 v[34:49], v[66:69], v[98:101], v[34:49]
	v_mfma_f32_32x32x16_bf16 v[50:65], v[66:69], v[102:105], v[50:65]
	v_exp_f32_e32 v67, v82
	v_exp_f32_e32 v68, v83
	v_exp_f32_e32 v69, v84
	v_exp_f32_e32 v75, v85
	v_exp_f32_e32 v76, v86
	v_add_f32_e32 v66, 0, v67
	v_exp_f32_e32 v77, v87
	v_add_f32_e32 v66, v68, v66
	v_exp_f32_e32 v78, v88
	v_add_f32_e32 v66, v69, v66
	v_exp_f32_e32 v79, v89
	v_add_f32_e32 v66, v75, v66
	v_exp_f32_e32 v80, v90
	v_add_f32_e32 v66, v76, v66
	v_exp_f32_e32 v81, v91
	v_add_f32_e32 v66, v77, v66
	v_exp_f32_e32 v82, v92
	v_add_f32_e32 v66, v78, v66
	v_exp_f32_e32 v83, v93
	v_add_f32_e32 v66, v79, v66
	v_exp_f32_e32 v84, v94
	v_add_f32_e32 v66, v80, v66
	v_exp_f32_e32 v85, v95
	v_add_f32_e32 v66, v81, v66
	v_exp_f32_e32 v86, v96
	v_add_f32_e32 v66, v82, v66
	v_exp_f32_e32 v87, v97
	v_add_f32_e32 v66, v83, v66
	v_add_f32_e32 v66, v84, v66
	v_add_f32_e32 v66, v85, v66
	v_add_f32_e32 v66, v86, v66
	v_add_f32_e32 v66, v87, v66
	v_add_f32_e32 v66, v66, v106
	v_cvt_pk_bf16_f32 v74, v67, v68
	v_cvt_pk_bf16_f32 v75, v69, v75
	v_cvt_pk_bf16_f32 v76, v76, v77
	v_cvt_pk_bf16_f32 v77, v78, v79
	v_cvt_pk_bf16_f32 v78, v80, v81
	v_cvt_pk_bf16_f32 v79, v82, v83
	v_cvt_pk_bf16_f32 v80, v84, v85
	v_cvt_pk_bf16_f32 v81, v86, v87
	s_nop 0
	v_permlane32_swap_b32_e32 v74, v76
	v_permlane32_swap_b32_e32 v75, v77
	v_permlane32_swap_b32_e32 v78, v80
	v_permlane32_swap_b32_e32 v79, v81
	ds_read_b64_tr_b16 v[82:83], v141 offset:0x1000
	ds_read_b64_tr_b16 v[84:85], v141 offset:0x1800
	ds_read_b64_tr_b16 v[86:87], v141 offset:0x1200
	ds_read_b64_tr_b16 v[88:89], v141 offset:0x1a00
	ds_read_b64_tr_b16 v[90:91], v141 offset:0x1400
	ds_read_b64_tr_b16 v[92:93], v141 offset:0x1c00
	ds_read_b64_tr_b16 v[94:95], v141 offset:0x1600
	ds_read_b64_tr_b16 v[96:97], v141 offset:0x1e00
	s_waitcnt lgkmcnt(0)
	s_nop 0
	v_mfma_f32_32x32x16_bf16 v[2:17], v[70:73], v[82:85], v[2:17]
	ds_read_b64_tr_b16 v[82:83], v141 offset:0x2000
	ds_read_b64_tr_b16 v[84:85], v141 offset:0x2800
	v_mfma_f32_32x32x16_bf16 v[18:33], v[70:73], v[86:89], v[18:33]
	ds_read_b64_tr_b16 v[86:87], v141 offset:0x2200
	ds_read_b64_tr_b16 v[88:89], v141 offset:0x2a00
	v_mfma_f32_32x32x16_bf16 v[34:49], v[70:73], v[90:93], v[34:49]
	ds_read_b64_tr_b16 v[90:91], v141 offset:0x2400
	ds_read_b64_tr_b16 v[92:93], v141 offset:0x2c00
	ds_read_b64_tr_b16 v[98:99], v141 offset:0x2600
	ds_read_b64_tr_b16 v[100:101], v141 offset:0x2e00
	s_waitcnt lgkmcnt(0)
	v_mfma_f32_32x32x16_bf16 v[50:65], v[70:73], v[94:97], v[50:65]
	ds_read_b64_tr_b16 v[68:69], v141 offset:0x3000
	ds_read_b64_tr_b16 v[70:71], v141 offset:0x3800
	v_mfma_f32_32x32x16_bf16 v[2:17], v[74:77], v[82:85], v[2:17]
	ds_read_b64_tr_b16 v[82:83], v141 offset:0x3200
	ds_read_b64_tr_b16 v[84:85], v141 offset:0x3a00
	v_mfma_f32_32x32x16_bf16 v[18:33], v[74:77], v[86:89], v[18:33]
	ds_read_b64_tr_b16 v[86:87], v141 offset:0x3400
	ds_read_b64_tr_b16 v[88:89], v141 offset:0x3c00
	v_mfma_f32_32x32x16_bf16 v[34:49], v[74:77], v[90:93], v[34:49]
	ds_read_b64_tr_b16 v[90:91], v141 offset:0x3600
	ds_read_b64_tr_b16 v[92:93], v141 offset:0x3e00
	s_waitcnt lgkmcnt(0)
	v_mfma_f32_32x32x16_bf16 v[50:65], v[74:77], v[98:101], v[50:65]
	v_mfma_f32_32x32x16_bf16 v[2:17], v[78:81], v[68:71], v[2:17]
	v_mov_b32_e32 v67, v66
	s_nop 1
	v_permlane32_swap_b32_e32 v66, v67
	v_cmp_gt_u32_e32 vcc, 32, v145
	v_mfma_f32_32x32x16_bf16 v[18:33], v[78:81], v[82:85], v[18:33]
	v_mfma_f32_32x32x16_bf16 v[34:49], v[78:81], v[86:89], v[34:49]
	v_mfma_f32_32x32x16_bf16 v[50:65], v[78:81], v[90:93], v[50:65]
	s_and_saveexec_b64 s[10:11], vcc
	s_cbranch_execz .LBB0_529
	v_add_f32_e32 v66, v66, v67
	v_lshl_add_u32 v67, v153, 2, v143
	ds_write_b32 v67, v66 offset:49152
	s_branch .LBB0_529
